# prologue row pass prefetches the next row's x while normalising the current row
# speedup vs baseline: 1.0179x; 1.0012x over previous
; __device__ __forceinline__ unsigned cvtpk(float lo, float hi) { f32x2_t v = {lo, hi}; bf16x2_t b = __builtin_convertvector(v, bf16x2_t); return __builtin_bit_cast(unsigned, b); }
; __device__ __forceinline__ float bflo(unsigned u) { return __uint_as_float(u << 16); }
; __device__ __forceinline__ float bfhi(unsigned u) { return __uint_as_float(u & 0xffff0000u); }
; __device__ __forceinline__ void row_pass(const float* xsrc, float* xdst, const bf16* F, float coef, const float* g_post, const float* g_pre, bf16* XN, int gw, int NGW, int lane) {
;     for (int m = gw; m < M; m += NGW) {
;         const f32x4* xr = (const f32x4*)(xsrc + (size_t)m * D) + lane;
;         f32x4 v[4];
; #pragma unroll
;         for (int j = 0; j < 4; ++j) v[j] = xr[64 * j];
;         if (F) {
;             const u32x2* fr = (const u32x2*)(F + (size_t)m * D) + lane; f32x4 f[4]; float ss = 0.f;
; #pragma unroll
;             for (int j = 0; j < 4; ++j) { const u32x2 w = fr[64 * j]; f[j] = (f32x4){bflo(w.x), bfhi(w.x), bflo(w.y), bfhi(w.y)}; ss += (f[j].x * f[j].x + f[j].y * f[j].y) + (f[j].z * f[j].z + f[j].w * f[j].w); }
;             const float rs = coef / sqrtf(wave_sum(ss, lane) * (1.f / D) + 1e-6f);
; #pragma unroll
;             for (int j = 0; j < 4; ++j) { const f32x4 g = ((const f32x4*)g_post)[lane + 64 * j]; v[j] = v[j] + f[j] * g * rs; }
;         }
;         u32x2* xo = (u32x2*)((bf16*)xdst + (size_t)m * D) + lane;
; #pragma unroll
;         for (int j = 0; j < 4; ++j) { u32x2 w; w.x = cvtpk(v[j].x, v[j].y); w.y = cvtpk(v[j].z, v[j].w); xo[64 * j] = w; }
;         if (XN) {
;             float ss = 0.f;
; #pragma unroll
;             for (int j = 0; j < 4; ++j) ss += (v[j].x * v[j].x + v[j].y * v[j].y) + (v[j].z * v[j].z + v[j].w * v[j].w);
;             const float rs = 1.0f / sqrtf(wave_sum(ss, lane) * (1.f / D) + 1e-6f);
;             u32x2* o8 = (u32x2*)(XN + (size_t)m * D) + lane;
; #pragma unroll
;             for (int j = 0; j < 4; ++j) { const f32x4 g = ((const f32x4*)g_pre)[lane + 64 * j]; const f32x4 y = v[j] * g * rs; u32x2 w; w.x = cvtpk(y.x, y.y); w.y = cvtpk(y.z, y.w); o8[64 * j] = w; }
;         }
.LBB0_516:
	s_or_b64 exec, exec, s[2:3]
	s_cmpk_gt_i32 s10, 0x3fff
	s_cbranch_scc1 .LBB0_7
	s_load_dwordx4 s[4:7], s[78:79], 0x0
	v_lshlrev_b32_e32 v0, 2, v3
	v_xor_b32_e32 v12, 4, v0
	v_xor_b32_e32 v13, 8, v0
	v_xor_b32_e32 v14, 16, v0
	v_xor_b32_e32 v15, 32, v0
	v_xor_b32_e32 v16, 64, v0
	v_xor_b32_e32 v17, 0x80, v0
	v_lshlrev_b32_e32 v0, 4, v3
	s_ashr_i32 s2, s11, 31
	s_ashr_i32 s3, s1, 31
	s_waitcnt lgkmcnt(0)
	v_lshl_add_u64 v[6:7], s[6:7], 0, v[0:1]
	s_add_u32 s6, s11, s1
	s_addc_u32 s7, s2, s3
	s_lshl_b64 s[2:3], s[6:7], 11
	s_add_u32 s2, s96, s2
	v_mov_b32_e32 v3, v1
	s_addc_u32 s3, s97, s3
	v_lshl_add_u64 v[2:3], s[2:3], 0, v[2:3]
	s_mov_b64 s[2:3], 0x11900600
	s_ashr_i32 s1, s0, 31
	v_lshl_add_u64 v[8:9], v[2:3], 0, s[2:3]
	s_lshl_b64 s[2:3], s[0:1], 11
	s_lshl_b64 s[6:7], s[6:7], 12
	s_add_u32 s4, s4, s6
	s_addc_u32 s5, s5, s7
	v_lshl_add_u64 v[2:3], s[4:5], 0, v[0:1]
	s_mov_b64 s[4:5], 0xc00
	v_lshl_add_u64 v[10:11], v[2:3], 0, s[4:5]
	s_lshl_b64 s[4:5], s[0:1], 12
	global_load_dwordx4 v[60:63], v[6:7], off
	global_load_dwordx4 v[64:67], v[6:7], off offset:1024
	global_load_dwordx4 v[68:71], v[6:7], off offset:2048
	global_load_dwordx4 v[72:75], v[6:7], off offset:3072
	s_waitcnt vmcnt(0)
	global_load_dwordx4 v[76:79], v[10:11], off offset:-3072
	global_load_dwordx4 v[80:83], v[10:11], off offset:-2048
	global_load_dwordx4 v[84:87], v[10:11], off offset:-1024
	global_load_dwordx4 v[88:91], v[10:11], off
.LBB0_518:
	s_waitcnt vmcnt(0)
	v_mov_b32_e32 v18, v76
	v_mov_b32_e32 v19, v77
	v_mov_b32_e32 v20, v78
	v_mov_b32_e32 v21, v79
	v_mov_b32_e32 v22, v80
	v_mov_b32_e32 v23, v81
	v_mov_b32_e32 v24, v82
	v_mov_b32_e32 v25, v83
	v_mov_b32_e32 v26, v84
	v_mov_b32_e32 v27, v85
	v_mov_b32_e32 v28, v86
	v_mov_b32_e32 v29, v87
	v_mov_b32_e32 v2, v88
	v_mov_b32_e32 v3, v89
	v_mov_b32_e32 v4, v90
	v_mov_b32_e32 v5, v91
	s_mov_b32 s1, 0xf8800000
	v_add_co_u32_e32 v34, vcc, s1, v8
	s_add_i32 s10, s10, s0
	s_nop 0
	v_addc_co_u32_e32 v35, vcc, -1, v9, vcc
	v_lshl_add_u64 v[10:11], v[10:11], 0, s[4:5]
	s_cmpk_lt_i32 s10, 0x4000
	s_cbranch_scc0 .Lrp_nopf
	global_load_dwordx4 v[76:79], v[10:11], off offset:-3072
	global_load_dwordx4 v[80:83], v[10:11], off offset:-2048
	global_load_dwordx4 v[84:87], v[10:11], off offset:-1024
	global_load_dwordx4 v[88:91], v[10:11], off
.Lrp_nopf:
	v_cvt_pk_bf16_f32 v30, v18, v19
	v_cvt_pk_bf16_f32 v31, v20, v21
	v_cvt_pk_bf16_f32 v32, v22, v23
	v_cvt_pk_bf16_f32 v33, v24, v25
	v_pk_mul_f32 v[40:41], v[20:21], v[20:21]
	v_pk_mul_f32 v[42:43], v[18:19], v[18:19]
	v_pk_mul_f32 v[44:45], v[24:25], v[24:25]
	v_pk_mul_f32 v[46:47], v[22:23], v[22:23]
	v_cvt_pk_bf16_f32 v36, v26, v27
	v_cvt_pk_bf16_f32 v37, v28, v29
	v_cvt_pk_bf16_f32 v38, v2, v3
	v_cvt_pk_bf16_f32 v39, v4, v5
	global_store_dwordx2 v[8:9], v[30:31], off offset:-1536
	global_store_dwordx2 v[8:9], v[32:33], off offset:-1024
	global_store_dwordx2 v[8:9], v[36:37], off offset:-512
	global_store_dwordx2 v[8:9], v[38:39], off
	v_pk_mov_b32 v[30:31], v[42:43], v[40:41] op_sel:[1,0]
	v_mov_b32_e32 v43, v41
	v_pk_mov_b32 v[32:33], v[46:47], v[44:45] op_sel:[1,0]
	v_mov_b32_e32 v47, v45
	v_pk_add_f32 v[40:41], v[30:31], v[42:43]
	v_pk_add_f32 v[42:43], v[32:33], v[46:47]
	v_mul_f32_e32 v49, v2, v2
	v_mul_f32_e32 v0, v27, v27
	v_mul_f32_e32 v48, v29, v29
	v_mul_f32_e32 v50, v3, v3
	v_mul_f32_e32 v51, v4, v4
	v_mul_f32_e32 v52, v5, v5
	v_pk_fma_f32 v[36:37], v[26:27], v[26:27], v[0:1] op_sel_hi:[1,1,0]
	v_pk_fma_f32 v[38:39], v[28:29], v[28:29], v[48:49] op_sel_hi:[1,1,0]
	v_pk_add_f32 v[40:41], v[40:41], v[40:41] op_sel:[0,1] op_sel_hi:[1,0]
	v_pk_add_f32 v[42:43], v[42:43], v[42:43] op_sel:[0,1] op_sel_hi:[1,0]
	v_mov_b32_e32 v37, v51
	v_mov_b32_e32 v39, v52
	v_mov_b32_e32 v41, v49
	v_mov_b32_e32 v43, v50
	v_pk_add_f32 v[36:37], v[36:37], v[38:39]
	v_pk_add_f32 v[38:39], v[40:41], v[42:43]
	v_lshl_add_u64 v[8:9], v[8:9], 0, s[2:3]
	v_pk_add_f32 v[36:37], v[38:39], v[36:37]
	v_pk_mul_f32 v[20:21], v[20:21], v[62:63]
	v_add_f32_e32 v0, v36, v37
	ds_bpermute_b32 v36, v12, v0
	v_pk_mul_f32 v[18:19], v[18:19], v[60:61]
	s_waitcnt lgkmcnt(0)
	v_add_f32_e32 v0, v0, v36
	ds_bpermute_b32 v36, v13, v0
	s_waitcnt lgkmcnt(0)
	v_add_f32_e32 v0, v0, v36
	ds_bpermute_b32 v36, v14, v0
	s_waitcnt lgkmcnt(0)
	v_add_f32_e32 v0, v0, v36
	ds_bpermute_b32 v36, v15, v0
	s_waitcnt lgkmcnt(0)
	v_add_f32_e32 v0, v0, v36
	ds_bpermute_b32 v36, v16, v0
	s_waitcnt lgkmcnt(0)
	v_add_f32_e32 v0, v0, v36
	ds_bpermute_b32 v36, v17, v0
	s_waitcnt lgkmcnt(0)
	v_add_f32_e32 v0, v0, v36
	v_fmamk_f32 v0, v0, 0x3a800000, v230
	v_mul_f32_e32 v36, 0x4f800000, v0
	v_cmp_gt_f32_e32 vcc, s80, v0
	s_nop 1
	v_cndmask_b32_e32 v0, v0, v36, vcc
	v_sqrt_f32_e32 v36, v0
	s_nop 0
	v_add_u32_e32 v37, -1, v36
	v_add_u32_e32 v38, 1, v36
	v_fma_f32 v39, -v37, v36, v0
	v_fma_f32 v40, -v38, v36, v0
	v_cmp_ge_f32_e64 s[6:7], 0, v39
	s_nop 1
	v_cndmask_b32_e64 v36, v36, v37, s[6:7]
	v_cmp_lt_f32_e64 s[6:7], 0, v40
	s_nop 1
	v_cndmask_b32_e64 v36, v36, v38, s[6:7]
	v_mul_f32_e32 v37, 0x37800000, v36
	v_cndmask_b32_e32 v36, v36, v37, vcc
	v_cmp_class_f32_e32 vcc, v0, v231
	s_nop 1
	v_cndmask_b32_e32 v0, v36, v0, vcc
	v_div_scale_f32 v36, s[6:7], v0, v0, 1.0
	v_rcp_f32_e32 v38, v36
	v_div_scale_f32 v37, vcc, 1.0, v0, 1.0
	v_fma_f32 v39, -v36, v38, 1.0
	v_fmac_f32_e32 v38, v39, v38
	v_mul_f32_e32 v39, v37, v38
	v_fma_f32 v40, -v36, v39, v37
	v_fmac_f32_e32 v39, v40, v38
	v_fma_f32 v36, -v36, v39, v37
	v_div_fmas_f32 v36, v36, v38, v39
	v_div_fixup_f32 v0, v36, v0, 1.0
	v_pk_mul_f32 v[20:21], v[20:21], v[0:1] op_sel_hi:[1,0]
	v_pk_mul_f32 v[18:19], v[18:19], v[0:1] op_sel_hi:[1,0]
	s_nop 0
	v_cvt_pk_bf16_f32 v18, v18, v19
	v_cvt_pk_bf16_f32 v19, v20, v21
	global_store_dwordx2 v[34:35], v[18:19], off offset:-1536
	v_pk_mul_f32 v[20:21], v[24:25], v[66:67]
	v_pk_mul_f32 v[18:19], v[22:23], v[64:65]
	v_pk_mul_f32 v[20:21], v[20:21], v[0:1] op_sel_hi:[1,0]
	v_pk_mul_f32 v[18:19], v[18:19], v[0:1] op_sel_hi:[1,0]
	s_nop 0
	v_cvt_pk_bf16_f32 v18, v18, v19
	v_cvt_pk_bf16_f32 v19, v20, v21
	global_store_dwordx2 v[34:35], v[18:19], off offset:-1024
	v_pk_mul_f32 v[20:21], v[28:29], v[70:71]
	v_pk_mul_f32 v[18:19], v[26:27], v[68:69]
	v_pk_mul_f32 v[20:21], v[20:21], v[0:1] op_sel_hi:[1,0]
	v_pk_mul_f32 v[18:19], v[18:19], v[0:1] op_sel_hi:[1,0]
	s_nop 0
	v_cvt_pk_bf16_f32 v18, v18, v19
	v_cvt_pk_bf16_f32 v19, v20, v21
	global_store_dwordx2 v[34:35], v[18:19], off offset:-512
	v_pk_mul_f32 v[4:5], v[4:5], v[74:75]
	v_pk_mul_f32 v[2:3], v[2:3], v[72:73]
	v_pk_mul_f32 v[4:5], v[0:1], v[4:5] op_sel_hi:[0,1]
	v_pk_mul_f32 v[2:3], v[0:1], v[2:3] op_sel_hi:[0,1]
	v_cvt_pk_bf16_f32 v2, v2, v3
	v_cvt_pk_bf16_f32 v3, v4, v5
	global_store_dwordx2 v[34:35], v[2:3], off
	s_cbranch_scc1 .LBB0_518
	s_branch .LBB0_7
